# attention epilogue gain-load ladder issued up front; conv LayerNorm wave sums via DPP + permlane swaps instead of ds_bpermute
# speedup vs baseline: 1.1141x; 1.0099x over previous
; #define LAS __attribute__((address_space(3)))
; __device__ __forceinline__ float bf_lo(unsigned w) { return __uint_as_float(w << 16); }
; __device__ __forceinline__ float bf_hi(unsigned w) { return __uint_as_float(w & 0xffff0000u); }
; __device__ __forceinline__ float silu_(float x) { return x * sigmoid_(x); }
; __device__ __forceinline__ u32x4 pack8(f32x4 a, f32x4 b) { u32x4 w; w.x = cvt_pk_bf16(a[0], a[1]); w.y = cvt_pk_bf16(a[2], a[3]); w.z = cvt_pk_bf16(b[0], b[1]); w.w = cvt_pk_bf16(b[2], b[3]); return w; }
; __device__ __forceinline__ float sumsq8(f32x4 a, f32x4 b) { return (a[0] * a[0] + a[1] * a[1]) + (a[2] * a[2] + a[3] * a[3]) + (b[0] * b[0] + b[1] * b[1]) + (b[2] * b[2] + b[3] * b[3]); }
; __device__ __forceinline__ float wave_sum(float v) {
; #pragma unroll
;     for (int o = 1; o < 64; o <<= 1) v += __shfl_xor(v, o);
;     return v;
; }
; __device__ __forceinline__ void conv_phase(KParams& P, int l, LAS unsigned char* lds) {
;     ...
;         for (int ti = 0; ti < 4; ++ti) { const int tt = wave + 8 * ti; if (tt >= ntok) break; const size_t row = rowbase + tt;
;             f32x4 v[2]; v[0] = *(const LAS f32x4*)(vL + tt * VL_PITCH + c0); v[1] = *(const LAS f32x4*)(vL + tt * VL_PITCH + c0 + 4);
;             const float mean = wave_sum((v[0][0] + v[0][1]) + (v[0][2] + v[0][3]) + (v[1][0] + v[1][1]) + (v[1][2] + v[1][3])) * (1.0f / 512.0f);
;             v[0] = v[0] - mean; v[1] = v[1] - mean;
;             const float var = wave_sum(sumsq8(v[0], v[1])) * (1.0f / 512.0f); const float rstd = rsqrtf(var + EPS);
;             const u32x4 gq = gqp[ti]; const float gcv[8] = {bf_lo(gq.x), bf_hi(gq.x), bf_lo(gq.y), bf_hi(gq.y), bf_lo(gq.z), bf_hi(gq.z), bf_lo(gq.w), bf_hi(gq.w)};
; #pragma unroll
;             for (int e = 0; e < 2; ++e)
; #pragma unroll
;                 for (int q = 0; q < 4; ++q) { const float y = v[e][q] * rstd * lg[e][q] + lb[e][q]; v[e][q] = silu_(y) * gcv[4 * e + q]; }
;             const float rs = rsqrtf(wave_sum(sumsq8(v[0], v[1])) * (1.0f / 512.0f) + EPS);
;             *(u32x4*)(cat + row * DM + 512 + c0) = pack8(v[0] * rs * lc[0], v[1] * rs * lc[1]);
.LBB0_647:
	v_cmp_gt_i32_e32 vcc, s0, v120
	s_waitcnt lgkmcnt(0)
	s_barrier
	s_and_saveexec_b64 s[2:3], vcc
	s_cbranch_execz .LBB0_516
	v_lshl_add_u64 v[44:45], s[60:61], 0, v[120:121]
	v_lshlrev_b64 v[24:25], 10, v[44:45]
	v_lshl_add_u64 v[36:37], v[134:135], 0, v[24:25]
	v_add_co_u32_e32 v24, vcc, 0x2000, v36
	v_add_u32_e32 v40, v227, v236
	s_nop 0
	v_addc_co_u32_e32 v25, vcc, 0, v37, vcc
	global_load_dwordx4 v[32:35], v[24:25], off
	v_add_co_u32_e32 v24, vcc, 0x4000, v36
	s_nop 1
	v_addc_co_u32_e32 v25, vcc, 0, v37, vcc
	global_load_dwordx4 v[28:31], v[24:25], off
	v_add_co_u32_e32 v24, vcc, 0x6000, v36
	s_nop 1
	v_addc_co_u32_e32 v25, vcc, 0, v37, vcc
	global_load_dwordx4 v[24:27], v[24:25], off
	s_nop 0
	global_load_dwordx4 v[36:39], v[36:37], off
	ds_read_b128 v[52:55], v40 offset:63488
	ds_read_b128 v[40:43], v40 offset:63504
	s_waitcnt lgkmcnt(1)
	v_mov_b32_e32 v46, v53
	v_mov_b32_e32 v47, v54
	v_mov_b32_e32 v48, v52
	v_mov_b32_e32 v49, v55
	v_pk_add_f32 v[46:47], v[46:47], v[48:49]
	s_waitcnt lgkmcnt(0)
	v_mov_b32_e32 v48, v42
	v_mov_b32_e32 v49, v40
	v_mov_b32_e32 v50, v43
	v_mov_b32_e32 v51, v41
	v_pk_add_f32 v[48:49], v[48:49], v[50:51]
	v_add_f32_e32 v46, v46, v47
	v_add_f32_e32 v46, v46, v49
	v_add_f32_e32 v47, v48, v46
	v_and_b32_e32 v46, 64, v214
	v_add_u32_e32 v51, 64, v46
	v_xor_b32_e32 v46, 1, v214
	v_cmp_lt_i32_e32 vcc, v46, v51
	s_nop 1
	v_cndmask_b32_e32 v46, v214, v46, vcc
	v_lshlrev_b32_e32 v46, 2, v46
	s_nop 1
	s_waitcnt lgkmcnt(0)
	v_add_f32_dpp v48, v47, v47 quad_perm:[1,0,3,2] row_mask:0xf bank_mask:0xf
	v_xor_b32_e32 v47, 2, v214
	v_cmp_lt_i32_e32 vcc, v47, v51
	s_nop 1
	v_cndmask_b32_e32 v47, v214, v47, vcc
	v_lshlrev_b32_e32 v47, 2, v47
	s_nop 1
	s_waitcnt lgkmcnt(0)
	v_add_f32_dpp v49, v48, v48 quad_perm:[2,3,0,1] row_mask:0xf bank_mask:0xf
	v_xor_b32_e32 v48, 4, v214
	v_cmp_lt_i32_e32 vcc, v48, v51
	s_nop 1
	v_cndmask_b32_e32 v48, v214, v48, vcc
	v_lshlrev_b32_e32 v48, 2, v48
	s_nop 1
	s_waitcnt lgkmcnt(0)
	v_add_f32_dpp v50, v49, v49 row_half_mirror row_mask:0xf bank_mask:0xf
	v_xor_b32_e32 v49, 8, v214
	v_cmp_lt_i32_e32 vcc, v49, v51
	s_nop 1
	v_cndmask_b32_e32 v49, v214, v49, vcc
	v_lshlrev_b32_e32 v49, 2, v49
	s_nop 1
	s_waitcnt lgkmcnt(0)
	v_add_f32_dpp v156, v50, v50 row_mirror row_mask:0xf bank_mask:0xf
	v_xor_b32_e32 v50, 16, v214
	v_cmp_lt_i32_e32 vcc, v50, v51
	s_nop 1
	v_cndmask_b32_e32 v50, v214, v50, vcc
	v_lshlrev_b32_e32 v50, 2, v50
	s_nop 0
	s_waitcnt lgkmcnt(0)
	v_mov_b32_e32 v180, v156
	s_nop 1
	v_permlane16_swap_b32_e32 v156, v180
	v_add_f32_e32 v156, v156, v180
	v_xor_b32_e32 v180, 32, v214
	v_cmp_lt_i32_e32 vcc, v180, v51
	s_nop 1
	v_cndmask_b32_e32 v51, v214, v180, vcc
	v_lshlrev_b32_e32 v51, 2, v51
	s_nop 0
	s_waitcnt lgkmcnt(0)
	v_mov_b32_e32 v180, v156
	s_nop 1
	v_permlane32_swap_b32_e32 v156, v180
	v_add_f32_e32 v156, v156, v180
	v_fmamk_f32 v53, v156, 0xbb000000, v53
	v_fmamk_f32 v52, v156, 0xbb000000, v52
	v_fmamk_f32 v55, v156, 0xbb000000, v55
	v_fmac_f32_e32 v54, 0xbb000000, v156
	v_pk_mul_f32 v[180:181], v[54:55], v[54:55]
	v_pk_mul_f32 v[182:183], v[52:53], v[52:53]
	v_fmamk_f32 v41, v156, 0xbb000000, v41
	v_fmamk_f32 v40, v156, 0xbb000000, v40
	v_fmamk_f32 v43, v156, 0xbb000000, v43
	v_fmac_f32_e32 v42, 0xbb000000, v156
	v_pk_mov_b32 v[184:185], v[182:183], v[180:181] op_sel:[1,0]
	v_mov_b32_e32 v183, v181
	v_pk_add_f32 v[180:181], v[184:185], v[182:183]
	v_pk_mul_f32 v[182:183], v[42:43], v[42:43]
	v_pk_mul_f32 v[184:185], v[40:41], v[40:41]
	v_mov_b32_e32 v186, v182
	v_mov_b32_e32 v187, v184
	v_mov_b32_e32 v184, v183
	v_pk_add_f32 v[182:183], v[186:187], v[184:185]
	v_add_f32_e32 v156, v180, v181
	v_add_f32_e32 v156, v183, v156
	v_add_f32_e32 v156, v182, v156
	s_nop 1
	s_waitcnt vmcnt(0)
	v_and_b32_e32 v181, 0xffff0000, v36
	s_waitcnt lgkmcnt(0)
	v_add_f32_dpp v156, v156, v156 quad_perm:[1,0,3,2] row_mask:0xf bank_mask:0xf
	s_nop 1
	s_waitcnt lgkmcnt(0)
	v_add_f32_dpp v156, v156, v156 quad_perm:[2,3,0,1] row_mask:0xf bank_mask:0xf
	s_nop 1
	s_waitcnt lgkmcnt(0)
	v_add_f32_dpp v156, v156, v156 row_half_mirror row_mask:0xf bank_mask:0xf
	s_nop 1
	s_waitcnt lgkmcnt(0)
	v_add_f32_dpp v156, v156, v156 row_mirror row_mask:0xf bank_mask:0xf
	s_nop 0
	s_waitcnt lgkmcnt(0)
	v_mov_b32_e32 v180, v156
	s_nop 1
	v_permlane16_swap_b32_e32 v156, v180
	v_add_f32_e32 v156, v156, v180
	s_nop 0
	s_waitcnt lgkmcnt(0)
; __device__ __forceinline__ float bf_lo(unsigned w) { return __uint_as_float(w << 16); }
; __device__ __forceinline__ float bf_hi(unsigned w) { return __uint_as_float(w & 0xffff0000u); }
; __device__ __forceinline__ float silu_(float x) { return x * sigmoid_(x); }
; __device__ __forceinline__ u32x4 pack8(f32x4 a, f32x4 b) { u32x4 w; w.x = cvt_pk_bf16(a[0], a[1]); w.y = cvt_pk_bf16(a[2], a[3]); w.z = cvt_pk_bf16(b[0], b[1]); w.w = cvt_pk_bf16(b[2], b[3]); return w; }
; __device__ __forceinline__ float sumsq8(f32x4 a, f32x4 b) { return (a[0] * a[0] + a[1] * a[1]) + (a[2] * a[2] + a[3] * a[3]) + (b[0] * b[0] + b[1] * b[1]) + (b[2] * b[2] + b[3] * b[3]); }
; __device__ __forceinline__ void conv_phase(KParams& P, int l, LAS unsigned char* lds) {
;     ...
;             const float mean = wave_sum((v[0][0] + v[0][1]) + (v[0][2] + v[0][3]) + (v[1][0] + v[1][1]) + (v[1][2] + v[1][3])) * (1.0f / 512.0f);
;             v[0] = v[0] - mean; v[1] = v[1] - mean;
;             const float var = wave_sum(sumsq8(v[0], v[1])) * (1.0f / 512.0f); const float rstd = rsqrtf(var + EPS);
;             const u32x4 gq = gqp[ti]; const float gcv[8] = {bf_lo(gq.x), bf_hi(gq.x), bf_lo(gq.y), bf_hi(gq.y), bf_lo(gq.z), bf_hi(gq.z), bf_lo(gq.w), bf_hi(gq.w)};
; #pragma unroll
;             for (int e = 0; e < 2; ++e)
; #pragma unroll
;                 for (int q = 0; q < 4; ++q) { const float y = v[e][q] * rstd * lg[e][q] + lb[e][q]; v[e][q] = silu_(y) * gcv[4 * e + q]; }
;             const float rs = rsqrtf(wave_sum(sumsq8(v[0], v[1])) * (1.0f / 512.0f) + EPS);
;             *(u32x4*)(cat + row * DM + 512 + c0) = pack8(v[0] * rs * lc[0], v[1] * rs * lc[1]);
	v_mov_b32_e32 v180, v156
	s_nop 1
	v_permlane32_swap_b32_e32 v156, v180
	v_add_f32_e32 v156, v156, v180
	v_fmamk_f32 v156, v156, 0x3b000000, v215
	v_cmp_gt_f32_e32 vcc, s87, v156
	v_mul_f32_e32 v180, 0x4b800000, v156
	s_nop 0
	v_cndmask_b32_e32 v156, v156, v180, vcc
	v_rsq_f32_e32 v156, v156
	s_nop 0
	v_mul_f32_e32 v180, 0x45800000, v156
	v_cndmask_b32_e32 v156, v156, v180, vcc
	v_pk_mul_f32 v[52:53], v[52:53], v[156:157] op_sel_hi:[1,0]
	v_lshlrev_b32_e32 v180, 16, v36
	v_pk_fma_f32 v[52:53], v[16:17], v[52:53], v[8:9]
	v_pk_mul_f32 v[54:55], v[54:55], v[156:157] op_sel_hi:[1,0]
	v_mul_f32_e32 v36, 0xbfb8aa3b, v52
	v_exp_f32_e32 v36, v36
	v_pk_fma_f32 v[54:55], v[18:19], v[54:55], v[10:11]
	v_pk_mul_f32 v[40:41], v[40:41], v[156:157] op_sel_hi:[1,0]
	v_pk_mul_f32 v[42:43], v[42:43], v[156:157] op_sel_hi:[1,0]
	v_add_f32_e32 v36, 1.0, v36
	v_rcp_f32_e32 v182, v36
	v_mul_f32_e32 v36, 0xbfb8aa3b, v53
	v_exp_f32_e32 v36, v36
	v_pk_fma_f32 v[40:41], v[20:21], v[40:41], v[12:13]
	v_pk_fma_f32 v[42:43], v[22:23], v[42:43], v[14:15]
	v_lshlrev_b32_e32 v156, 1, v122
	v_add_f32_e32 v36, 1.0, v36
	v_rcp_f32_e32 v183, v36
	v_lshlrev_b32_e32 v36, 16, v37
	v_and_b32_e32 v37, 0xffff0000, v37
	v_pk_mul_f32 v[52:53], v[52:53], v[182:183]
	s_nop 0
	v_pk_mul_f32 v[52:53], v[52:53], v[180:181]
	v_mul_f32_e32 v180, 0xbfb8aa3b, v54
	v_mul_f32_e32 v181, 0xbfb8aa3b, v55
	v_exp_f32_e32 v180, v180
	v_exp_f32_e32 v181, v181
	v_add_f32_e32 v180, 1.0, v180
	v_add_f32_e32 v181, 1.0, v181
	v_rcp_f32_e32 v180, v180
	v_rcp_f32_e32 v181, v181
	s_nop 0
	v_pk_mul_f32 v[54:55], v[54:55], v[180:181]
	s_nop 0
	v_pk_mul_f32 v[36:37], v[54:55], v[36:37]
	v_lshlrev_b32_e32 v54, 16, v38
	v_and_b32_e32 v55, 0xffff0000, v38
	v_mul_f32_e32 v38, 0xbfb8aa3b, v40
	v_exp_f32_e32 v38, v38
	s_nop 0
	v_add_f32_e32 v38, 1.0, v38
	v_rcp_f32_e32 v180, v38
	v_mul_f32_e32 v38, 0xbfb8aa3b, v41
	v_exp_f32_e32 v38, v38
	s_nop 0
	v_add_f32_e32 v38, 1.0, v38
	v_rcp_f32_e32 v181, v38
	v_lshlrev_b32_e32 v38, 16, v39
	v_and_b32_e32 v39, 0xffff0000, v39
	v_pk_mul_f32 v[40:41], v[40:41], v[180:181]
	s_nop 0
	v_pk_mul_f32 v[40:41], v[40:41], v[54:55]
	v_mul_f32_e32 v54, 0xbfb8aa3b, v42
	v_mul_f32_e32 v55, 0xbfb8aa3b, v43
	v_exp_f32_e32 v54, v54
	v_exp_f32_e32 v55, v55
	v_mov_b32_e32 v181, v41
	v_add_f32_e32 v54, 1.0, v54
	v_add_f32_e32 v55, 1.0, v55
	v_rcp_f32_e32 v54, v54
	v_rcp_f32_e32 v55, v55
	s_nop 0
	v_pk_mul_f32 v[42:43], v[42:43], v[54:55]
	s_nop 0
	v_pk_mul_f32 v[38:39], v[42:43], v[38:39]
	v_mov_b32_e32 v54, v53
	v_mov_b32_e32 v55, v37
	v_mov_b32_e32 v42, v52
	v_mov_b32_e32 v43, v36
	v_pk_mul_f32 v[54:55], v[54:55], v[54:55]
	v_mov_b32_e32 v180, v39
	v_pk_fma_f32 v[42:43], v[42:43], v[42:43], v[54:55]
	v_mov_b32_e32 v54, v38
	v_mov_b32_e32 v55, v40
	v_pk_mul_f32 v[180:181], v[180:181], v[180:181]
	v_add_f32_e32 v42, v42, v43
	v_pk_fma_f32 v[54:55], v[54:55], v[54:55], v[180:181]
	s_nop 0
	v_add_f32_e32 v42, v55, v42
	v_add_f32_e32 v42, v54, v42
	s_nop 1
	s_waitcnt lgkmcnt(0)
	v_add_f32_dpp v42, v42, v42 quad_perm:[1,0,3,2] row_mask:0xf bank_mask:0xf
	s_nop 1
	s_waitcnt lgkmcnt(0)
	v_add_f32_dpp v42, v42, v42 quad_perm:[2,3,0,1] row_mask:0xf bank_mask:0xf
	s_nop 1
	s_waitcnt lgkmcnt(0)
	v_add_f32_dpp v42, v42, v42 row_half_mirror row_mask:0xf bank_mask:0xf
	s_nop 1
	s_waitcnt lgkmcnt(0)
	v_add_f32_dpp v42, v42, v42 row_mirror row_mask:0xf bank_mask:0xf
	s_nop 0
	s_waitcnt lgkmcnt(0)
	v_mov_b32_e32 v43, v42
	s_nop 1
	v_permlane16_swap_b32_e32 v42, v43
	v_add_f32_e32 v42, v42, v43
	s_nop 0
	s_waitcnt lgkmcnt(0)
	v_mov_b32_e32 v43, v42
	s_nop 1
	v_permlane32_swap_b32_e32 v42, v43
	v_add_f32_e32 v42, v42, v43
	v_fmamk_f32 v42, v42, 0x3b000000, v215
	v_cmp_gt_f32_e32 vcc, s87, v42
	v_mul_f32_e32 v43, 0x4b800000, v42
	s_nop 0
	v_cndmask_b32_e32 v42, v42, v43, vcc
	v_rsq_f32_e32 v42, v42
	s_nop 0
	v_mul_f32_e32 v43, 0x45800000, v42
	v_cndmask_b32_e32 v42, v42, v43, vcc
	v_pk_mul_f32 v[40:41], v[40:41], v[42:43] op_sel_hi:[1,0]
	v_pk_mul_f32 v[38:39], v[38:39], v[42:43] op_sel_hi:[1,0]
	v_pk_mul_f32 v[52:53], v[52:53], v[42:43] op_sel_hi:[1,0]
	v_pk_mul_f32 v[36:37], v[36:37], v[42:43] op_sel_hi:[1,0]
	v_pk_mul_f32 v[42:43], v[2:3], v[38:39]
	v_pk_mul_f32 v[38:39], v[0:1], v[40:41]
	v_lshlrev_b64 v[40:41], 11, v[44:45]
	v_lshl_add_u64 v[40:41], s[62:63], 0, v[40:41]
	v_lshl_add_u64 v[40:41], v[40:41], 0, v[156:157]
	v_add_co_u32_e32 v40, vcc, 0x22d00000, v40
	v_pk_mul_f32 v[54:55], v[6:7], v[36:37]
	v_pk_mul_f32 v[36:37], v[4:5], v[52:53]
	v_addc_co_u32_e32 v41, vcc, 0, v41, vcc
	v_cvt_pk_bf16_f32 v36, v36, v37
	v_cvt_pk_bf16_f32 v37, v54, v55
	v_cvt_pk_bf16_f32 v38, v38, v39
	v_cvt_pk_bf16_f32 v39, v42, v43
	v_cmp_gt_i32_e32 vcc, s0, v172
	global_store_dwordx4 v[40:41], v[36:39], off offset:1024
	s_and_b64 exec, exec, vcc
	s_cbranch_execz .LBB0_516
; #define LAS __attribute__((address_space(3)))
; __device__ __forceinline__ float bf_lo(unsigned w) { return __uint_as_float(w << 16); }
; __device__ __forceinline__ float bf_hi(unsigned w) { return __uint_as_float(w & 0xffff0000u); }
; __device__ __forceinline__ float silu_(float x) { return x * sigmoid_(x); }
; __device__ __forceinline__ u32x4 pack8(f32x4 a, f32x4 b) { u32x4 w; w.x = cvt_pk_bf16(a[0], a[1]); w.y = cvt_pk_bf16(a[2], a[3]); w.z = cvt_pk_bf16(b[0], b[1]); w.w = cvt_pk_bf16(b[2], b[3]); return w; }
; __device__ __forceinline__ float sumsq8(f32x4 a, f32x4 b) { return (a[0] * a[0] + a[1] * a[1]) + (a[2] * a[2] + a[3] * a[3]) + (b[0] * b[0] + b[1] * b[1]) + (b[2] * b[2] + b[3] * b[3]); }
; __device__ __forceinline__ void conv_phase(KParams& P, int l, LAS unsigned char* lds) {
;     ...
;         for (int ti = 0; ti < 4; ++ti) { const int tt = wave + 8 * ti; if (tt >= ntok) break; const size_t row = rowbase + tt;
;             f32x4 v[2]; v[0] = *(const LAS f32x4*)(vL + tt * VL_PITCH + c0); v[1] = *(const LAS f32x4*)(vL + tt * VL_PITCH + c0 + 4);
;             const float mean = wave_sum((v[0][0] + v[0][1]) + (v[0][2] + v[0][3]) + (v[1][0] + v[1][1]) + (v[1][2] + v[1][3])) * (1.0f / 512.0f);
;             v[0] = v[0] - mean; v[1] = v[1] - mean;
;             const float var = wave_sum(sumsq8(v[0], v[1])) * (1.0f / 512.0f); const float rstd = rsqrtf(var + EPS);
;             const u32x4 gq = gqp[ti]; const float gcv[8] = {bf_lo(gq.x), bf_hi(gq.x), bf_lo(gq.y), bf_hi(gq.y), bf_lo(gq.z), bf_hi(gq.z), bf_lo(gq.w), bf_hi(gq.w)};
; #pragma unroll
;             for (int e = 0; e < 2; ++e)
; #pragma unroll
;                 for (int q = 0; q < 4; ++q) { const float y = v[e][q] * rstd * lg[e][q] + lb[e][q]; v[e][q] = silu_(y) * gcv[4 * e + q]; }
;             const float rs = rsqrtf(wave_sum(sumsq8(v[0], v[1])) * (1.0f / 512.0f) + EPS);
;             *(u32x4*)(cat + row * DM + 512 + c0) = pack8(v[0] * rs * lc[0], v[1] * rs * lc[1]);
	ds_read_b128 v[42:45], v237 offset:63488
	ds_read_b128 v[36:39], v237 offset:63504
	s_waitcnt lgkmcnt(1)
	v_mov_b32_e32 v40, v43
	v_mov_b32_e32 v41, v44
	v_mov_b32_e32 v52, v42
	v_mov_b32_e32 v53, v45
	v_pk_add_f32 v[40:41], v[40:41], v[52:53]
	s_waitcnt lgkmcnt(0)
	v_mov_b32_e32 v52, v38
	v_mov_b32_e32 v53, v36
	v_mov_b32_e32 v54, v39
	v_mov_b32_e32 v55, v37
	v_pk_add_f32 v[52:53], v[52:53], v[54:55]
	v_add_f32_e32 v40, v40, v41
	v_add_f32_e32 v40, v40, v53
	v_add_f32_e32 v40, v52, v40
	s_nop 1
	s_waitcnt lgkmcnt(0)
	v_add_f32_dpp v40, v40, v40 quad_perm:[1,0,3,2] row_mask:0xf bank_mask:0xf
	s_nop 1
	s_waitcnt lgkmcnt(0)
	v_add_f32_dpp v40, v40, v40 quad_perm:[2,3,0,1] row_mask:0xf bank_mask:0xf
	s_nop 1
	s_waitcnt lgkmcnt(0)
	v_add_f32_dpp v40, v40, v40 row_half_mirror row_mask:0xf bank_mask:0xf
	s_nop 1
	s_waitcnt lgkmcnt(0)
	v_add_f32_dpp v40, v40, v40 row_mirror row_mask:0xf bank_mask:0xf
	s_nop 0
	s_waitcnt lgkmcnt(0)
	v_mov_b32_e32 v41, v40
	s_nop 1
	v_permlane16_swap_b32_e32 v40, v41
	v_add_f32_e32 v40, v40, v41
	s_nop 0
	s_waitcnt lgkmcnt(0)
	v_mov_b32_e32 v54, v40
	v_mov_b32_e32 v41, v40
	s_nop 1
	v_permlane32_swap_b32_e32 v54, v41
	v_add_f32_e32 v54, v54, v41
	v_fmamk_f32 v53, v54, 0xbb000000, v43
	v_fmamk_f32 v52, v54, 0xbb000000, v42
	v_fmamk_f32 v45, v54, 0xbb000000, v45
	v_fmac_f32_e32 v44, 0xbb000000, v54
	v_fmamk_f32 v41, v54, 0xbb000000, v37
	v_fmamk_f32 v40, v54, 0xbb000000, v36
	v_pk_mul_f32 v[36:37], v[44:45], v[44:45]
	v_pk_mul_f32 v[42:43], v[52:53], v[52:53]
	v_fmamk_f32 v39, v54, 0xbb000000, v39
	v_fmac_f32_e32 v38, 0xbb000000, v54
	v_pk_mov_b32 v[54:55], v[42:43], v[36:37] op_sel:[1,0]
	v_mov_b32_e32 v43, v37
	v_pk_add_f32 v[36:37], v[54:55], v[42:43]
	v_pk_mul_f32 v[42:43], v[38:39], v[38:39]
	v_pk_mul_f32 v[54:55], v[40:41], v[40:41]
	v_mov_b32_e32 v180, v42
	v_mov_b32_e32 v181, v54
	v_mov_b32_e32 v54, v43
	v_pk_add_f32 v[42:43], v[180:181], v[54:55]
	v_add_f32_e32 v36, v36, v37
	v_add_f32_e32 v36, v43, v36
	v_add_f32_e32 v36, v42, v36
	s_nop 1
	s_waitcnt lgkmcnt(0)
	v_add_f32_dpp v36, v36, v36 quad_perm:[1,0,3,2] row_mask:0xf bank_mask:0xf
	s_nop 1
	s_waitcnt lgkmcnt(0)
	v_add_f32_dpp v36, v36, v36 quad_perm:[2,3,0,1] row_mask:0xf bank_mask:0xf
	s_nop 1
	s_waitcnt lgkmcnt(0)
	v_add_f32_dpp v36, v36, v36 row_half_mirror row_mask:0xf bank_mask:0xf
	s_nop 1
	s_waitcnt lgkmcnt(0)
	v_add_f32_dpp v36, v36, v36 row_mirror row_mask:0xf bank_mask:0xf
	s_nop 0
	s_waitcnt lgkmcnt(0)
	v_mov_b32_e32 v37, v36
	s_nop 1
	v_permlane16_swap_b32_e32 v36, v37
	v_add_f32_e32 v36, v36, v37
	s_nop 0
	s_waitcnt lgkmcnt(0)
	v_mov_b32_e32 v37, v36
	s_nop 1
	v_permlane32_swap_b32_e32 v36, v37
	v_add_f32_e32 v36, v36, v37
	v_fmamk_f32 v36, v36, 0x3b000000, v215
	v_cmp_gt_f32_e32 vcc, s87, v36
	v_mul_f32_e32 v37, 0x4b800000, v36
	s_nop 0
	v_cndmask_b32_e32 v36, v36, v37, vcc
	v_rsq_f32_e32 v36, v36
	s_nop 0
	v_mul_f32_e32 v37, 0x45800000, v36
	v_cndmask_b32_e32 v42, v36, v37, vcc
	v_pk_mul_f32 v[52:53], v[52:53], v[42:43] op_sel_hi:[1,0]
	v_lshlrev_b32_e32 v36, 16, v32
	v_pk_fma_f32 v[52:53], v[16:17], v[52:53], v[8:9]
	v_and_b32_e32 v37, 0xffff0000, v32
	v_mul_f32_e32 v32, 0xbfb8aa3b, v52
	v_exp_f32_e32 v32, v32
	v_pk_mul_f32 v[44:45], v[44:45], v[42:43] op_sel_hi:[1,0]
	v_add_f32_e32 v32, 1.0, v32
	v_rcp_f32_e32 v54, v32
	v_mul_f32_e32 v32, 0xbfb8aa3b, v53
	v_exp_f32_e32 v32, v32
	v_pk_fma_f32 v[44:45], v[18:19], v[44:45], v[10:11]
	v_add_f32_e32 v32, 1.0, v32
	v_mul_f32_e32 v43, 0xbfb8aa3b, v44
	v_rcp_f32_e32 v55, v32
	v_exp_f32_e32 v43, v43
	v_lshlrev_b32_e32 v32, 16, v33
	v_and_b32_e32 v33, 0xffff0000, v33
	v_pk_mul_f32 v[52:53], v[52:53], v[54:55]
	v_add_f32_e32 v43, 1.0, v43
	v_pk_mul_f32 v[36:37], v[52:53], v[36:37]
	v_rcp_f32_e32 v52, v43
	v_mul_f32_e32 v43, 0xbfb8aa3b, v45
	v_exp_f32_e32 v43, v43
	s_nop 0
	v_add_f32_e32 v43, 1.0, v43
	v_rcp_f32_e32 v53, v43
	v_pk_mul_f32 v[40:41], v[40:41], v[42:43] op_sel_hi:[1,0]
	v_pk_mul_f32 v[38:39], v[38:39], v[42:43] op_sel_hi:[1,0]
	v_pk_fma_f32 v[40:41], v[20:21], v[40:41], v[12:13]
	v_pk_mul_f32 v[44:45], v[44:45], v[52:53]
	v_pk_fma_f32 v[38:39], v[22:23], v[38:39], v[14:15]
	v_pk_mul_f32 v[32:33], v[44:45], v[32:33]
	v_lshlrev_b32_e32 v44, 16, v34
	v_and_b32_e32 v45, 0xffff0000, v34
	v_mul_f32_e32 v34, 0xbfb8aa3b, v40
	v_exp_f32_e32 v34, v34
	v_mul_f32_e32 v42, 0xbfb8aa3b, v38
	v_mul_f32_e32 v43, 0xbfb8aa3b, v39
	v_exp_f32_e32 v42, v42
	v_add_f32_e32 v34, 1.0, v34
	v_rcp_f32_e32 v52, v34
	v_mul_f32_e32 v34, 0xbfb8aa3b, v41
	v_exp_f32_e32 v34, v34
	v_exp_f32_e32 v43, v43
	v_add_f32_e32 v42, 1.0, v42
	v_rcp_f32_e32 v42, v42
	v_add_f32_e32 v34, 1.0, v34
	v_add_f32_e32 v43, 1.0, v43
	v_rcp_f32_e32 v53, v34
	v_rcp_f32_e32 v43, v43
	v_lshlrev_b32_e32 v34, 16, v35
	v_and_b32_e32 v35, 0xffff0000, v35
	v_pk_mul_f32 v[40:41], v[40:41], v[52:53]
	v_pk_mul_f32 v[38:39], v[38:39], v[42:43]
	v_pk_mul_f32 v[40:41], v[40:41], v[44:45]
	v_pk_mul_f32 v[34:35], v[38:39], v[34:35]
	v_mov_b32_e32 v44, v37
	v_mov_b32_e32 v45, v33
	v_mov_b32_e32 v42, v36
	v_mov_b32_e32 v43, v32
	v_pk_mul_f32 v[44:45], v[44:45], v[44:45]
	v_mov_b32_e32 v52, v35
	v_mov_b32_e32 v53, v41
	v_pk_fma_f32 v[42:43], v[42:43], v[42:43], v[44:45]
	v_mov_b32_e32 v44, v34
	v_mov_b32_e32 v45, v40
	v_pk_mul_f32 v[52:53], v[52:53], v[52:53]
	v_add_f32_e32 v42, v42, v43
	v_pk_fma_f32 v[44:45], v[44:45], v[44:45], v[52:53]
	v_lshl_add_u64 v[38:39], s[60:61], 0, v[172:173]
	v_add_f32_e32 v42, v45, v42
	v_add_f32_e32 v42, v44, v42
	s_nop 1
	s_waitcnt lgkmcnt(0)
	v_add_f32_dpp v42, v42, v42 quad_perm:[1,0,3,2] row_mask:0xf bank_mask:0xf
	s_nop 1
	s_waitcnt lgkmcnt(0)
	v_add_f32_dpp v42, v42, v42 quad_perm:[2,3,0,1] row_mask:0xf bank_mask:0xf
	s_nop 1
	s_waitcnt lgkmcnt(0)
; #define LAS __attribute__((address_space(3)))
; __device__ __forceinline__ float bf_lo(unsigned w) { return __uint_as_float(w << 16); }
; __device__ __forceinline__ float bf_hi(unsigned w) { return __uint_as_float(w & 0xffff0000u); }
; __device__ __forceinline__ float silu_(float x) { return x * sigmoid_(x); }
; __device__ __forceinline__ u32x4 pack8(f32x4 a, f32x4 b) { u32x4 w; w.x = cvt_pk_bf16(a[0], a[1]); w.y = cvt_pk_bf16(a[2], a[3]); w.z = cvt_pk_bf16(b[0], b[1]); w.w = cvt_pk_bf16(b[2], b[3]); return w; }
; __device__ __forceinline__ float sumsq8(f32x4 a, f32x4 b) { return (a[0] * a[0] + a[1] * a[1]) + (a[2] * a[2] + a[3] * a[3]) + (b[0] * b[0] + b[1] * b[1]) + (b[2] * b[2] + b[3] * b[3]); }
; __device__ __forceinline__ void conv_phase(KParams& P, int l, LAS unsigned char* lds) {
;     ...
;         for (int ti = 0; ti < 4; ++ti) { const int tt = wave + 8 * ti; if (tt >= ntok) break; const size_t row = rowbase + tt;
;             f32x4 v[2]; v[0] = *(const LAS f32x4*)(vL + tt * VL_PITCH + c0); v[1] = *(const LAS f32x4*)(vL + tt * VL_PITCH + c0 + 4);
;             const float mean = wave_sum((v[0][0] + v[0][1]) + (v[0][2] + v[0][3]) + (v[1][0] + v[1][1]) + (v[1][2] + v[1][3])) * (1.0f / 512.0f);
;             v[0] = v[0] - mean; v[1] = v[1] - mean;
;             const float var = wave_sum(sumsq8(v[0], v[1])) * (1.0f / 512.0f); const float rstd = rsqrtf(var + EPS);
;             const u32x4 gq = gqp[ti]; const float gcv[8] = {bf_lo(gq.x), bf_hi(gq.x), bf_lo(gq.y), bf_hi(gq.y), bf_lo(gq.z), bf_hi(gq.z), bf_lo(gq.w), bf_hi(gq.w)};
; #pragma unroll
;             for (int e = 0; e < 2; ++e)
; #pragma unroll
;                 for (int q = 0; q < 4; ++q) { const float y = v[e][q] * rstd * lg[e][q] + lb[e][q]; v[e][q] = silu_(y) * gcv[4 * e + q]; }
;             const float rs = rsqrtf(wave_sum(sumsq8(v[0], v[1])) * (1.0f / 512.0f) + EPS);
;             *(u32x4*)(cat + row * DM + 512 + c0) = pack8(v[0] * rs * lc[0], v[1] * rs * lc[1]);
	v_add_f32_dpp v42, v42, v42 row_half_mirror row_mask:0xf bank_mask:0xf
	s_nop 1
	s_waitcnt lgkmcnt(0)
	v_add_f32_dpp v42, v42, v42 row_mirror row_mask:0xf bank_mask:0xf
	s_nop 0
	s_waitcnt lgkmcnt(0)
	v_mov_b32_e32 v43, v42
	s_nop 1
	v_permlane16_swap_b32_e32 v42, v43
	v_add_f32_e32 v42, v42, v43
	s_nop 0
	s_waitcnt lgkmcnt(0)
	v_mov_b32_e32 v43, v42
	s_nop 1
	v_permlane32_swap_b32_e32 v42, v43
	v_add_f32_e32 v42, v42, v43
	v_fmamk_f32 v42, v42, 0x3b000000, v215
	v_cmp_gt_f32_e32 vcc, s87, v42
	v_mul_f32_e32 v43, 0x4b800000, v42
	s_nop 0
	v_cndmask_b32_e32 v42, v42, v43, vcc
	v_rsq_f32_e32 v42, v42
	s_nop 0
	v_mul_f32_e32 v43, 0x45800000, v42
	v_cndmask_b32_e32 v42, v42, v43, vcc
	v_pk_mul_f32 v[36:37], v[36:37], v[42:43] op_sel_hi:[1,0]
	v_pk_mul_f32 v[32:33], v[32:33], v[42:43] op_sel_hi:[1,0]
	v_pk_mul_f32 v[34:35], v[34:35], v[42:43] op_sel_hi:[1,0]
	v_pk_mul_f32 v[44:45], v[6:7], v[32:33]
	v_pk_mul_f32 v[32:33], v[4:5], v[36:37]
	v_pk_mul_f32 v[36:37], v[40:41], v[42:43] op_sel_hi:[1,0]
	v_pk_mul_f32 v[40:41], v[2:3], v[34:35]
	v_pk_mul_f32 v[34:35], v[0:1], v[36:37]
	v_lshlrev_b64 v[36:37], 11, v[38:39]
	v_lshl_add_u64 v[36:37], s[62:63], 0, v[36:37]
	v_lshl_add_u64 v[36:37], v[36:37], 0, v[156:157]
	v_add_co_u32_e32 v36, vcc, 0x22d00000, v36
	v_cvt_pk_bf16_f32 v32, v32, v33
	s_nop 0
	v_addc_co_u32_e32 v37, vcc, 0, v37, vcc
	v_cvt_pk_bf16_f32 v33, v44, v45
	v_cvt_pk_bf16_f32 v34, v34, v35
	v_cvt_pk_bf16_f32 v35, v40, v41
	v_cmp_gt_i32_e32 vcc, s0, v174
	global_store_dwordx4 v[36:37], v[32:35], off offset:1024
	s_and_b64 exec, exec, vcc
	s_cbranch_execz .LBB0_516
	ds_read_b128 v[38:41], v238 offset:63488
	ds_read_b128 v[32:35], v238 offset:63504
	s_waitcnt lgkmcnt(1)
	v_mov_b32_e32 v36, v39
	v_mov_b32_e32 v37, v40
	v_mov_b32_e32 v42, v38
	v_mov_b32_e32 v43, v41
	v_pk_add_f32 v[36:37], v[36:37], v[42:43]
	s_waitcnt lgkmcnt(0)
	v_mov_b32_e32 v42, v34
	v_mov_b32_e32 v43, v32
	v_mov_b32_e32 v44, v35
	v_mov_b32_e32 v45, v33
	v_pk_add_f32 v[42:43], v[42:43], v[44:45]
	v_add_f32_e32 v36, v36, v37
	v_add_f32_e32 v36, v36, v43
	v_add_f32_e32 v36, v42, v36
	s_nop 1
	s_waitcnt lgkmcnt(0)
	v_add_f32_dpp v36, v36, v36 quad_perm:[1,0,3,2] row_mask:0xf bank_mask:0xf
	s_nop 1
	s_waitcnt lgkmcnt(0)
	v_add_f32_dpp v36, v36, v36 quad_perm:[2,3,0,1] row_mask:0xf bank_mask:0xf
	s_nop 1
	s_waitcnt lgkmcnt(0)
	v_add_f32_dpp v36, v36, v36 row_half_mirror row_mask:0xf bank_mask:0xf
	s_nop 1
	s_waitcnt lgkmcnt(0)
	v_add_f32_dpp v36, v36, v36 row_mirror row_mask:0xf bank_mask:0xf
	s_nop 0
	s_waitcnt lgkmcnt(0)
	v_mov_b32_e32 v37, v36
	s_nop 1
	v_permlane16_swap_b32_e32 v36, v37
	v_add_f32_e32 v36, v36, v37
	s_nop 0
	s_waitcnt lgkmcnt(0)
	v_mov_b32_e32 v44, v36
	v_mov_b32_e32 v37, v36
	s_nop 1
	v_permlane32_swap_b32_e32 v44, v37
	v_add_f32_e32 v44, v44, v37
	v_fmamk_f32 v43, v44, 0xbb000000, v39
	v_fmamk_f32 v42, v44, 0xbb000000, v38
	v_fmamk_f32 v41, v44, 0xbb000000, v41
	v_fmac_f32_e32 v40, 0xbb000000, v44
	v_fmamk_f32 v37, v44, 0xbb000000, v33
	v_fmamk_f32 v36, v44, 0xbb000000, v32
	v_pk_mul_f32 v[32:33], v[40:41], v[40:41]
	v_pk_mul_f32 v[38:39], v[42:43], v[42:43]
	v_fmamk_f32 v35, v44, 0xbb000000, v35
	v_fmac_f32_e32 v34, 0xbb000000, v44
	v_pk_mov_b32 v[44:45], v[38:39], v[32:33] op_sel:[1,0]
	v_mov_b32_e32 v39, v33
	v_pk_add_f32 v[32:33], v[44:45], v[38:39]
	v_pk_mul_f32 v[38:39], v[34:35], v[34:35]
	v_pk_mul_f32 v[44:45], v[36:37], v[36:37]
	v_mov_b32_e32 v52, v38
	v_mov_b32_e32 v53, v44
	v_mov_b32_e32 v44, v39
	v_pk_add_f32 v[38:39], v[52:53], v[44:45]
	v_add_f32_e32 v32, v32, v33
	v_add_f32_e32 v32, v39, v32
	v_add_f32_e32 v32, v38, v32
	s_nop 1
	s_waitcnt lgkmcnt(0)
	v_add_f32_dpp v32, v32, v32 quad_perm:[1,0,3,2] row_mask:0xf bank_mask:0xf
	s_nop 1
	s_waitcnt lgkmcnt(0)
	v_add_f32_dpp v32, v32, v32 quad_perm:[2,3,0,1] row_mask:0xf bank_mask:0xf
	s_nop 1
	s_waitcnt lgkmcnt(0)
	v_add_f32_dpp v32, v32, v32 row_half_mirror row_mask:0xf bank_mask:0xf
	s_nop 1
	s_waitcnt lgkmcnt(0)
	v_add_f32_dpp v32, v32, v32 row_mirror row_mask:0xf bank_mask:0xf
	s_nop 0
	s_waitcnt lgkmcnt(0)
	v_mov_b32_e32 v33, v32
	s_nop 1
	v_permlane16_swap_b32_e32 v32, v33
	v_add_f32_e32 v32, v32, v33
	s_nop 0
	s_waitcnt lgkmcnt(0)
	v_mov_b32_e32 v33, v32
	s_nop 1
	v_permlane32_swap_b32_e32 v32, v33
	v_add_f32_e32 v32, v32, v33
	v_fmamk_f32 v32, v32, 0x3b000000, v215
	v_cmp_gt_f32_e32 vcc, s87, v32
	v_mul_f32_e32 v33, 0x4b800000, v32
	s_nop 0
	v_cndmask_b32_e32 v32, v32, v33, vcc
	v_rsq_f32_e32 v32, v32
	s_nop 0
	v_mul_f32_e32 v33, 0x45800000, v32
	v_cndmask_b32_e32 v38, v32, v33, vcc
	v_pk_mul_f32 v[42:43], v[42:43], v[38:39] op_sel_hi:[1,0]
	v_lshlrev_b32_e32 v32, 16, v28
	v_pk_fma_f32 v[42:43], v[16:17], v[42:43], v[8:9]
	v_and_b32_e32 v33, 0xffff0000, v28
	v_mul_f32_e32 v28, 0xbfb8aa3b, v42
	v_exp_f32_e32 v28, v28
	v_pk_mul_f32 v[40:41], v[40:41], v[38:39] op_sel_hi:[1,0]
	v_add_f32_e32 v28, 1.0, v28
	v_rcp_f32_e32 v44, v28
	v_mul_f32_e32 v28, 0xbfb8aa3b, v43
	v_exp_f32_e32 v28, v28
	v_pk_fma_f32 v[40:41], v[18:19], v[40:41], v[10:11]
	v_add_f32_e32 v28, 1.0, v28
	v_mul_f32_e32 v39, 0xbfb8aa3b, v40
	v_rcp_f32_e32 v45, v28
	v_exp_f32_e32 v39, v39
	v_lshlrev_b32_e32 v28, 16, v29
	v_and_b32_e32 v29, 0xffff0000, v29
	v_pk_mul_f32 v[42:43], v[42:43], v[44:45]
	v_add_f32_e32 v39, 1.0, v39
	v_pk_mul_f32 v[32:33], v[42:43], v[32:33]
	v_rcp_f32_e32 v42, v39
	v_mul_f32_e32 v39, 0xbfb8aa3b, v41
	v_exp_f32_e32 v39, v39
	s_nop 0
	v_add_f32_e32 v39, 1.0, v39
	v_rcp_f32_e32 v43, v39
	v_pk_mul_f32 v[36:37], v[36:37], v[38:39] op_sel_hi:[1,0]
	v_pk_mul_f32 v[34:35], v[34:35], v[38:39] op_sel_hi:[1,0]
	v_pk_fma_f32 v[36:37], v[20:21], v[36:37], v[12:13]
	v_pk_mul_f32 v[40:41], v[40:41], v[42:43]
; #define LAS __attribute__((address_space(3)))
; __device__ __forceinline__ float bf_lo(unsigned w) { return __uint_as_float(w << 16); }
; __device__ __forceinline__ float bf_hi(unsigned w) { return __uint_as_float(w & 0xffff0000u); }
; __device__ __forceinline__ float silu_(float x) { return x * sigmoid_(x); }
; __device__ __forceinline__ u32x4 pack8(f32x4 a, f32x4 b) { u32x4 w; w.x = cvt_pk_bf16(a[0], a[1]); w.y = cvt_pk_bf16(a[2], a[3]); w.z = cvt_pk_bf16(b[0], b[1]); w.w = cvt_pk_bf16(b[2], b[3]); return w; }
; __device__ __forceinline__ float sumsq8(f32x4 a, f32x4 b) { return (a[0] * a[0] + a[1] * a[1]) + (a[2] * a[2] + a[3] * a[3]) + (b[0] * b[0] + b[1] * b[1]) + (b[2] * b[2] + b[3] * b[3]); }
; __device__ __forceinline__ void conv_phase(KParams& P, int l, LAS unsigned char* lds) {
;     ...
;         for (int ti = 0; ti < 4; ++ti) { const int tt = wave + 8 * ti; if (tt >= ntok) break; const size_t row = rowbase + tt;
;             f32x4 v[2]; v[0] = *(const LAS f32x4*)(vL + tt * VL_PITCH + c0); v[1] = *(const LAS f32x4*)(vL + tt * VL_PITCH + c0 + 4);
;             const float mean = wave_sum((v[0][0] + v[0][1]) + (v[0][2] + v[0][3]) + (v[1][0] + v[1][1]) + (v[1][2] + v[1][3])) * (1.0f / 512.0f);
;             v[0] = v[0] - mean; v[1] = v[1] - mean;
;             const float var = wave_sum(sumsq8(v[0], v[1])) * (1.0f / 512.0f); const float rstd = rsqrtf(var + EPS);
;             const u32x4 gq = gqp[ti]; const float gcv[8] = {bf_lo(gq.x), bf_hi(gq.x), bf_lo(gq.y), bf_hi(gq.y), bf_lo(gq.z), bf_hi(gq.z), bf_lo(gq.w), bf_hi(gq.w)};
; #pragma unroll
;             for (int e = 0; e < 2; ++e)
; #pragma unroll
;                 for (int q = 0; q < 4; ++q) { const float y = v[e][q] * rstd * lg[e][q] + lb[e][q]; v[e][q] = silu_(y) * gcv[4 * e + q]; }
;             const float rs = rsqrtf(wave_sum(sumsq8(v[0], v[1])) * (1.0f / 512.0f) + EPS);
;             *(u32x4*)(cat + row * DM + 512 + c0) = pack8(v[0] * rs * lc[0], v[1] * rs * lc[1]);
	v_pk_fma_f32 v[34:35], v[22:23], v[34:35], v[14:15]
	v_pk_mul_f32 v[28:29], v[40:41], v[28:29]
	v_lshlrev_b32_e32 v40, 16, v30
	v_and_b32_e32 v41, 0xffff0000, v30
	v_mul_f32_e32 v30, 0xbfb8aa3b, v36
	v_exp_f32_e32 v30, v30
	v_mul_f32_e32 v38, 0xbfb8aa3b, v34
	v_mul_f32_e32 v39, 0xbfb8aa3b, v35
	v_exp_f32_e32 v38, v38
	v_add_f32_e32 v30, 1.0, v30
	v_rcp_f32_e32 v42, v30
	v_mul_f32_e32 v30, 0xbfb8aa3b, v37
	v_exp_f32_e32 v30, v30
	v_exp_f32_e32 v39, v39
	v_add_f32_e32 v38, 1.0, v38
	v_rcp_f32_e32 v38, v38
	v_add_f32_e32 v30, 1.0, v30
	v_add_f32_e32 v39, 1.0, v39
	v_rcp_f32_e32 v43, v30
	v_rcp_f32_e32 v39, v39
	v_lshlrev_b32_e32 v30, 16, v31
	v_and_b32_e32 v31, 0xffff0000, v31
	v_pk_mul_f32 v[36:37], v[36:37], v[42:43]
	v_pk_mul_f32 v[34:35], v[34:35], v[38:39]
	v_pk_mul_f32 v[36:37], v[36:37], v[40:41]
	v_pk_mul_f32 v[30:31], v[34:35], v[30:31]
	v_mov_b32_e32 v40, v33
	v_mov_b32_e32 v41, v29
	v_mov_b32_e32 v38, v32
	v_mov_b32_e32 v39, v28
	v_pk_mul_f32 v[40:41], v[40:41], v[40:41]
	v_mov_b32_e32 v42, v31
	v_mov_b32_e32 v43, v37
	v_pk_fma_f32 v[38:39], v[38:39], v[38:39], v[40:41]
	v_mov_b32_e32 v40, v30
	v_mov_b32_e32 v41, v36
	v_pk_mul_f32 v[42:43], v[42:43], v[42:43]
	v_add_f32_e32 v38, v38, v39
	v_pk_fma_f32 v[40:41], v[40:41], v[40:41], v[42:43]
	v_lshl_add_u64 v[34:35], s[60:61], 0, v[174:175]
	v_add_f32_e32 v38, v41, v38
	v_add_f32_e32 v38, v40, v38
	s_nop 1
	s_waitcnt lgkmcnt(0)
	v_add_f32_dpp v38, v38, v38 quad_perm:[1,0,3,2] row_mask:0xf bank_mask:0xf
	s_nop 1
	s_waitcnt lgkmcnt(0)
	v_add_f32_dpp v38, v38, v38 quad_perm:[2,3,0,1] row_mask:0xf bank_mask:0xf
	s_nop 1
	s_waitcnt lgkmcnt(0)
	v_add_f32_dpp v38, v38, v38 row_half_mirror row_mask:0xf bank_mask:0xf
	s_nop 1
	s_waitcnt lgkmcnt(0)
	v_add_f32_dpp v38, v38, v38 row_mirror row_mask:0xf bank_mask:0xf
	s_nop 0
	s_waitcnt lgkmcnt(0)
	v_mov_b32_e32 v39, v38
	s_nop 1
	v_permlane16_swap_b32_e32 v38, v39
	v_add_f32_e32 v38, v38, v39
	s_nop 0
	s_waitcnt lgkmcnt(0)
	v_mov_b32_e32 v39, v38
	s_nop 1
	v_permlane32_swap_b32_e32 v38, v39
	v_add_f32_e32 v38, v38, v39
	v_fmamk_f32 v38, v38, 0x3b000000, v215
	v_cmp_gt_f32_e32 vcc, s87, v38
	v_mul_f32_e32 v39, 0x4b800000, v38
	s_nop 0
	v_cndmask_b32_e32 v38, v38, v39, vcc
	v_rsq_f32_e32 v38, v38
	s_nop 0
	v_mul_f32_e32 v39, 0x45800000, v38
	v_cndmask_b32_e32 v38, v38, v39, vcc
	v_pk_mul_f32 v[32:33], v[32:33], v[38:39] op_sel_hi:[1,0]
	v_pk_mul_f32 v[28:29], v[28:29], v[38:39] op_sel_hi:[1,0]
	v_pk_mul_f32 v[30:31], v[30:31], v[38:39] op_sel_hi:[1,0]
	v_pk_mul_f32 v[40:41], v[6:7], v[28:29]
	v_pk_mul_f32 v[28:29], v[4:5], v[32:33]
	v_pk_mul_f32 v[32:33], v[36:37], v[38:39] op_sel_hi:[1,0]
	v_pk_mul_f32 v[36:37], v[2:3], v[30:31]
	v_pk_mul_f32 v[30:31], v[0:1], v[32:33]
	v_lshlrev_b64 v[32:33], 11, v[34:35]
	v_lshl_add_u64 v[32:33], s[62:63], 0, v[32:33]
	v_lshl_add_u64 v[32:33], v[32:33], 0, v[156:157]
	v_add_co_u32_e32 v32, vcc, 0x22d00000, v32
	v_cvt_pk_bf16_f32 v28, v28, v29
	s_nop 0
	v_addc_co_u32_e32 v33, vcc, 0, v33, vcc
	v_cvt_pk_bf16_f32 v29, v40, v41
	v_cvt_pk_bf16_f32 v30, v30, v31
	v_cvt_pk_bf16_f32 v31, v36, v37
	v_cmp_gt_i32_e32 vcc, s0, v176
	global_store_dwordx4 v[32:33], v[28:31], off offset:1024
	s_and_b64 exec, exec, vcc
	s_cbranch_execz .LBB0_516
	ds_read_b128 v[34:37], v239 offset:63488
	ds_read_b128 v[28:31], v239 offset:63504
	s_waitcnt lgkmcnt(1)
	v_mov_b32_e32 v32, v35
	v_mov_b32_e32 v33, v36
	v_mov_b32_e32 v38, v34
	v_mov_b32_e32 v39, v37
	v_pk_add_f32 v[32:33], v[32:33], v[38:39]
	s_waitcnt lgkmcnt(0)
	v_mov_b32_e32 v38, v30
	v_mov_b32_e32 v39, v28
	v_mov_b32_e32 v40, v31
	v_mov_b32_e32 v41, v29
	v_pk_add_f32 v[38:39], v[38:39], v[40:41]
	v_add_f32_e32 v32, v32, v33
	v_add_f32_e32 v32, v32, v39
	v_add_f32_e32 v32, v38, v32
	s_nop 1
	s_waitcnt lgkmcnt(0)
	v_add_f32_dpp v32, v32, v32 quad_perm:[1,0,3,2] row_mask:0xf bank_mask:0xf
	s_nop 1
	s_waitcnt lgkmcnt(0)
	v_add_f32_dpp v32, v32, v32 quad_perm:[2,3,0,1] row_mask:0xf bank_mask:0xf
	s_nop 1
	s_waitcnt lgkmcnt(0)
	v_add_f32_dpp v32, v32, v32 row_half_mirror row_mask:0xf bank_mask:0xf
	s_nop 1
	s_waitcnt lgkmcnt(0)
	v_add_f32_dpp v32, v32, v32 row_mirror row_mask:0xf bank_mask:0xf
	s_nop 0
	s_waitcnt lgkmcnt(0)
	v_mov_b32_e32 v33, v32
	s_nop 1
	v_permlane16_swap_b32_e32 v32, v33
	v_add_f32_e32 v32, v32, v33
	s_nop 0
	s_waitcnt lgkmcnt(0)
	v_mov_b32_e32 v40, v32
	v_mov_b32_e32 v33, v32
	s_nop 1
	v_permlane32_swap_b32_e32 v40, v33
	v_add_f32_e32 v40, v40, v33
	v_fmamk_f32 v39, v40, 0xbb000000, v35
	v_fmamk_f32 v38, v40, 0xbb000000, v34
	v_fmamk_f32 v37, v40, 0xbb000000, v37
	v_fmac_f32_e32 v36, 0xbb000000, v40
	v_fmamk_f32 v33, v40, 0xbb000000, v29
	v_fmamk_f32 v32, v40, 0xbb000000, v28
	v_pk_mul_f32 v[28:29], v[36:37], v[36:37]
	v_pk_mul_f32 v[34:35], v[38:39], v[38:39]
	v_fmamk_f32 v31, v40, 0xbb000000, v31
	v_fmac_f32_e32 v30, 0xbb000000, v40
	v_pk_mov_b32 v[40:41], v[34:35], v[28:29] op_sel:[1,0]
	v_mov_b32_e32 v35, v29
	v_pk_add_f32 v[28:29], v[40:41], v[34:35]
	v_pk_mul_f32 v[34:35], v[30:31], v[30:31]
	v_pk_mul_f32 v[40:41], v[32:33], v[32:33]
	v_mov_b32_e32 v42, v34
	v_mov_b32_e32 v43, v40
	v_mov_b32_e32 v40, v35
	v_pk_add_f32 v[34:35], v[42:43], v[40:41]
	v_add_f32_e32 v28, v28, v29
	v_add_f32_e32 v28, v35, v28
	v_add_f32_e32 v28, v34, v28
	s_nop 1
	s_waitcnt lgkmcnt(0)
; #define LAS __attribute__((address_space(3)))
; __device__ __forceinline__ float bf_lo(unsigned w) { return __uint_as_float(w << 16); }
; __device__ __forceinline__ float bf_hi(unsigned w) { return __uint_as_float(w & 0xffff0000u); }
; __device__ __forceinline__ float silu_(float x) { return x * sigmoid_(x); }
; __device__ __forceinline__ u32x4 pack8(f32x4 a, f32x4 b) { u32x4 w; w.x = cvt_pk_bf16(a[0], a[1]); w.y = cvt_pk_bf16(a[2], a[3]); w.z = cvt_pk_bf16(b[0], b[1]); w.w = cvt_pk_bf16(b[2], b[3]); return w; }
; __device__ __forceinline__ float sumsq8(f32x4 a, f32x4 b) { return (a[0] * a[0] + a[1] * a[1]) + (a[2] * a[2] + a[3] * a[3]) + (b[0] * b[0] + b[1] * b[1]) + (b[2] * b[2] + b[3] * b[3]); }
; __device__ __forceinline__ void conv_phase(KParams& P, int l, LAS unsigned char* lds) {
;     ...
;         for (int ti = 0; ti < 4; ++ti) { const int tt = wave + 8 * ti; if (tt >= ntok) break; const size_t row = rowbase + tt;
;             f32x4 v[2]; v[0] = *(const LAS f32x4*)(vL + tt * VL_PITCH + c0); v[1] = *(const LAS f32x4*)(vL + tt * VL_PITCH + c0 + 4);
;             const float mean = wave_sum((v[0][0] + v[0][1]) + (v[0][2] + v[0][3]) + (v[1][0] + v[1][1]) + (v[1][2] + v[1][3])) * (1.0f / 512.0f);
;             v[0] = v[0] - mean; v[1] = v[1] - mean;
;             const float var = wave_sum(sumsq8(v[0], v[1])) * (1.0f / 512.0f); const float rstd = rsqrtf(var + EPS);
;             const u32x4 gq = gqp[ti]; const float gcv[8] = {bf_lo(gq.x), bf_hi(gq.x), bf_lo(gq.y), bf_hi(gq.y), bf_lo(gq.z), bf_hi(gq.z), bf_lo(gq.w), bf_hi(gq.w)};
; #pragma unroll
;             for (int e = 0; e < 2; ++e)
; #pragma unroll
;                 for (int q = 0; q < 4; ++q) { const float y = v[e][q] * rstd * lg[e][q] + lb[e][q]; v[e][q] = silu_(y) * gcv[4 * e + q]; }
;             const float rs = rsqrtf(wave_sum(sumsq8(v[0], v[1])) * (1.0f / 512.0f) + EPS);
;             *(u32x4*)(cat + row * DM + 512 + c0) = pack8(v[0] * rs * lc[0], v[1] * rs * lc[1]);
	v_add_f32_dpp v28, v28, v28 quad_perm:[1,0,3,2] row_mask:0xf bank_mask:0xf
	s_nop 1
	s_waitcnt lgkmcnt(0)
	v_add_f32_dpp v28, v28, v28 quad_perm:[2,3,0,1] row_mask:0xf bank_mask:0xf
	s_nop 1
	s_waitcnt lgkmcnt(0)
	v_add_f32_dpp v28, v28, v28 row_half_mirror row_mask:0xf bank_mask:0xf
	s_nop 1
	s_waitcnt lgkmcnt(0)
	v_add_f32_dpp v28, v28, v28 row_mirror row_mask:0xf bank_mask:0xf
	s_nop 0
	s_waitcnt lgkmcnt(0)
	v_mov_b32_e32 v29, v28
	s_nop 1
	v_permlane16_swap_b32_e32 v28, v29
	v_add_f32_e32 v28, v28, v29
	s_nop 0
	s_waitcnt lgkmcnt(0)
	v_mov_b32_e32 v29, v28
	s_nop 1
	v_permlane32_swap_b32_e32 v28, v29
	v_add_f32_e32 v28, v28, v29
	v_fmamk_f32 v28, v28, 0x3b000000, v215
	v_cmp_gt_f32_e32 vcc, s87, v28
	v_mul_f32_e32 v29, 0x4b800000, v28
	s_nop 0
	v_cndmask_b32_e32 v28, v28, v29, vcc
	v_rsq_f32_e32 v28, v28
	s_nop 0
	v_mul_f32_e32 v29, 0x45800000, v28
	v_cndmask_b32_e32 v34, v28, v29, vcc
	v_pk_mul_f32 v[38:39], v[38:39], v[34:35] op_sel_hi:[1,0]
	v_lshlrev_b32_e32 v28, 16, v24
	v_pk_fma_f32 v[38:39], v[16:17], v[38:39], v[8:9]
	v_and_b32_e32 v29, 0xffff0000, v24
	v_mul_f32_e32 v24, 0xbfb8aa3b, v38
	v_exp_f32_e32 v24, v24
	v_pk_mul_f32 v[36:37], v[36:37], v[34:35] op_sel_hi:[1,0]
	v_add_f32_e32 v24, 1.0, v24
	v_rcp_f32_e32 v40, v24
	v_mul_f32_e32 v24, 0xbfb8aa3b, v39
	v_exp_f32_e32 v24, v24
	v_pk_fma_f32 v[36:37], v[18:19], v[36:37], v[10:11]
	v_add_f32_e32 v24, 1.0, v24
	v_mul_f32_e32 v35, 0xbfb8aa3b, v36
	v_rcp_f32_e32 v41, v24
	v_exp_f32_e32 v35, v35
	v_lshlrev_b32_e32 v24, 16, v25
	v_and_b32_e32 v25, 0xffff0000, v25
	v_pk_mul_f32 v[38:39], v[38:39], v[40:41]
	v_add_f32_e32 v35, 1.0, v35
	v_pk_mul_f32 v[28:29], v[38:39], v[28:29]
	v_rcp_f32_e32 v38, v35
	v_mul_f32_e32 v35, 0xbfb8aa3b, v37
	v_exp_f32_e32 v35, v35
	s_nop 0
	v_add_f32_e32 v35, 1.0, v35
	v_rcp_f32_e32 v39, v35
	v_pk_mul_f32 v[32:33], v[32:33], v[34:35] op_sel_hi:[1,0]
	v_pk_mul_f32 v[30:31], v[30:31], v[34:35] op_sel_hi:[1,0]
	v_pk_fma_f32 v[32:33], v[20:21], v[32:33], v[12:13]
	v_pk_mul_f32 v[36:37], v[36:37], v[38:39]
	v_pk_fma_f32 v[30:31], v[22:23], v[30:31], v[14:15]
	v_pk_mul_f32 v[24:25], v[36:37], v[24:25]
	v_lshlrev_b32_e32 v36, 16, v26
	v_and_b32_e32 v37, 0xffff0000, v26
	v_mul_f32_e32 v26, 0xbfb8aa3b, v32
	v_exp_f32_e32 v26, v26
	v_mul_f32_e32 v34, 0xbfb8aa3b, v30
	v_mul_f32_e32 v35, 0xbfb8aa3b, v31
	v_exp_f32_e32 v34, v34
	v_add_f32_e32 v26, 1.0, v26
	v_rcp_f32_e32 v38, v26
	v_mul_f32_e32 v26, 0xbfb8aa3b, v33
	v_exp_f32_e32 v26, v26
	v_exp_f32_e32 v35, v35
	v_add_f32_e32 v34, 1.0, v34
	v_rcp_f32_e32 v34, v34
	v_add_f32_e32 v26, 1.0, v26
	v_add_f32_e32 v35, 1.0, v35
	v_rcp_f32_e32 v39, v26
	v_rcp_f32_e32 v35, v35
	v_lshlrev_b32_e32 v26, 16, v27
	v_and_b32_e32 v27, 0xffff0000, v27
	v_pk_mul_f32 v[32:33], v[32:33], v[38:39]
	v_pk_mul_f32 v[30:31], v[30:31], v[34:35]
	v_pk_mul_f32 v[32:33], v[32:33], v[36:37]
	v_pk_mul_f32 v[26:27], v[30:31], v[26:27]
	v_mov_b32_e32 v36, v29
	v_mov_b32_e32 v37, v25
	v_mov_b32_e32 v34, v28
	v_mov_b32_e32 v35, v24
	v_pk_mul_f32 v[36:37], v[36:37], v[36:37]
	v_mov_b32_e32 v38, v27
	v_mov_b32_e32 v39, v33
	v_pk_fma_f32 v[34:35], v[34:35], v[34:35], v[36:37]
	v_mov_b32_e32 v36, v26
	v_mov_b32_e32 v37, v32
	v_pk_mul_f32 v[38:39], v[38:39], v[38:39]
	v_add_f32_e32 v34, v34, v35
	v_pk_fma_f32 v[36:37], v[36:37], v[36:37], v[38:39]
	v_lshl_add_u64 v[30:31], s[60:61], 0, v[176:177]
	v_add_f32_e32 v34, v37, v34
	v_add_f32_e32 v34, v36, v34
	s_nop 1
	s_waitcnt lgkmcnt(0)
	v_add_f32_dpp v34, v34, v34 quad_perm:[1,0,3,2] row_mask:0xf bank_mask:0xf
	s_nop 1
	s_waitcnt lgkmcnt(0)
	v_add_f32_dpp v34, v34, v34 quad_perm:[2,3,0,1] row_mask:0xf bank_mask:0xf
	s_nop 1
	s_waitcnt lgkmcnt(0)
	v_add_f32_dpp v34, v34, v34 row_half_mirror row_mask:0xf bank_mask:0xf
	s_nop 1
	s_waitcnt lgkmcnt(0)
	v_add_f32_dpp v34, v34, v34 row_mirror row_mask:0xf bank_mask:0xf
	s_nop 0
	s_waitcnt lgkmcnt(0)
	v_mov_b32_e32 v35, v34
	s_nop 1
	v_permlane16_swap_b32_e32 v34, v35
	v_add_f32_e32 v34, v34, v35
	s_nop 0
	s_waitcnt lgkmcnt(0)
	v_mov_b32_e32 v35, v34
	s_nop 1
	v_permlane32_swap_b32_e32 v34, v35
	v_add_f32_e32 v34, v34, v35
	v_fmamk_f32 v34, v34, 0x3b000000, v215
	v_cmp_gt_f32_e32 vcc, s87, v34
	v_mul_f32_e32 v35, 0x4b800000, v34
	s_nop 0
	v_cndmask_b32_e32 v34, v34, v35, vcc
	v_rsq_f32_e32 v34, v34
	s_nop 0
	v_mul_f32_e32 v35, 0x45800000, v34
	v_cndmask_b32_e32 v34, v34, v35, vcc
	v_pk_mul_f32 v[28:29], v[28:29], v[34:35] op_sel_hi:[1,0]
	v_pk_mul_f32 v[24:25], v[24:25], v[34:35] op_sel_hi:[1,0]
	v_pk_mul_f32 v[26:27], v[26:27], v[34:35] op_sel_hi:[1,0]
	v_pk_mul_f32 v[36:37], v[6:7], v[24:25]
	v_pk_mul_f32 v[24:25], v[4:5], v[28:29]
	v_pk_mul_f32 v[28:29], v[32:33], v[34:35] op_sel_hi:[1,0]
	v_pk_mul_f32 v[32:33], v[2:3], v[26:27]
	v_pk_mul_f32 v[26:27], v[0:1], v[28:29]
	v_lshlrev_b64 v[28:29], 11, v[30:31]
	v_lshl_add_u64 v[28:29], s[62:63], 0, v[28:29]
	v_lshl_add_u64 v[28:29], v[28:29], 0, v[156:157]
	v_add_co_u32_e32 v28, vcc, 0x22d00000, v28
	v_cvt_pk_bf16_f32 v24, v24, v25
	v_cvt_pk_bf16_f32 v25, v36, v37
	v_cvt_pk_bf16_f32 v26, v26, v27
	v_cvt_pk_bf16_f32 v27, v32, v33
	v_addc_co_u32_e32 v29, vcc, 0, v29, vcc
	global_store_dwordx4 v[28:29], v[24:27], off offset:1024
	s_branch .LBB0_516

; __device__ __forceinline__ unsigned cvt_pk_bf16(float lo, float hi) { f32x2 v = {lo, hi}; bf16x2_t b = __builtin_convertvector(v, bf16x2_t); return __builtin_bit_cast(unsigned, b); }
; __device__ __forceinline__ void attn_unit(KParams& P, int l, const AUnit& U, LAS unsigned char* lds) {
;     ...
;     float tot = 0.f;
; #pragma unroll
;     for (int hh = 0; hh < 8; ++hh) tot += ssqL[hh * 32 + i];
;     const float rsa = rsqrtf(tot * (1.0f / 512.0f) + EPS);
;     const float* lna = P.in[17] + l * 512 + h * 64;
;     if (valid) {
; #pragma unroll
;         for (int vb = 0; vb < 2; ++vb)
; #pragma unroll
;             for (int rg = 0; rg < 4; ++rg) { const int v = 32 * vb + 8 * rg + 4 * hi; const f32x4 g4 = *(const f32x4*)(lna + v);
;                 u32x2 w; w.x = cvt_pk_bf16(oa[vb][4 * rg + 0] * rsa * g4[0], oa[vb][4 * rg + 1] * rsa * g4[1]); w.y = cvt_pk_bf16(oa[vb][4 * rg + 2] * rsa * g4[2], oa[vb][4 * rg + 3] * rsa * g4[3]);
;                 *(u32x2*)(cat + v) = w; }
;     }
.LBB0_690:
	s_or_b64 exec, exec, s[6:7]
	s_waitcnt lgkmcnt(0)
	s_barrier
	s_and_saveexec_b64 s[2:3], s[4:5]
	s_xor_b64 s[2:3], exec, s[2:3]
	s_mov_b64 s[88:89], s[92:93]
	s_cbranch_execz .LBB0_663
	s_lshl_b64 s[4:5], s[0:1], 2
	v_readlane_b32 s6, v255, 38
	v_lshlrev_b32_e32 v38, 2, v183
	s_add_u32 s4, s6, s4
	s_addc_u32 s5, s90, s5
	v_lshlrev_b32_e32 v39, 2, v38
	global_load_dwordx4 v[32:35], v39, s[4:5]
	global_load_dwordx4 v[192:195], v39, s[4:5] offset:32
	global_load_dwordx4 v[196:199], v39, s[4:5] offset:64
	global_load_dwordx4 v[200:203], v39, s[4:5] offset:96
	global_load_dwordx4 v[204:207], v39, s[4:5] offset:128
	global_load_dwordx4 v[208:211], v39, s[4:5] offset:160
	global_load_dwordx4 v[226:229], v39, s[4:5] offset:192
	global_load_dwordx4 v[232:235], v39, s[4:5] offset:224
	v_lshlrev_b32_e32 v40, 2, v181
	v_or_b32_e32 v41, 0x23400, v40
	v_or_b32_e32 v42, 0x23480, v40
	v_or_b32_e32 v43, 0x23500, v40
	v_or_b32_e32 v44, 0x23580, v40
	v_or_b32_e32 v45, 0x23600, v40
	v_or_b32_e32 v46, 0x23680, v40
	v_or_b32_e32 v47, 0x23700, v40
	v_or_b32_e32 v40, 0x23780, v40
	ds_read_b32 v41, v41
	ds_read_b32 v42, v42
	ds_read_b32 v43, v43
	ds_read_b32 v44, v44
	ds_read_b32 v45, v45
	ds_read_b32 v46, v46
	ds_read_b32 v47, v47
	ds_read_b32 v40, v40
	s_waitcnt lgkmcnt(7)
	v_add_f32_e32 v41, 0, v41
	s_waitcnt lgkmcnt(6)
	v_add_f32_e32 v41, v41, v42
	s_waitcnt lgkmcnt(5)
	v_add_f32_e32 v41, v41, v43
	s_waitcnt lgkmcnt(4)
	v_add_f32_e32 v41, v41, v44
	s_waitcnt lgkmcnt(3)
	v_add_f32_e32 v41, v41, v45
	s_waitcnt lgkmcnt(2)
	v_add_f32_e32 v41, v41, v46
	s_waitcnt lgkmcnt(1)
	v_add_f32_e32 v41, v41, v47
	s_waitcnt lgkmcnt(0)
	v_add_f32_e32 v40, v41, v40
	v_fmamk_f32 v40, v40, 0x3b000000, v215
	v_mul_f32_e32 v41, 0x4b800000, v40
	v_cmp_gt_f32_e32 vcc, s87, v40
	v_lshlrev_b32_e32 v156, 1, v38
	v_lshlrev_b64 v[36:37], 11, v[162:163]
	v_cndmask_b32_e32 v40, v40, v41, vcc
	v_rsq_f32_e32 v40, v40
	v_lshl_add_u64 v[36:37], s[74:75], 0, v[36:37]
	v_lshl_add_u64 v[36:37], s[0:1], 1, v[36:37]
	v_lshl_add_u64 v[36:37], v[36:37], 0, v[156:157]
	v_mul_f32_e32 v38, 0x45800000, v40
	v_cndmask_b32_e32 v38, v40, v38, vcc
	v_pk_mul_f32 v[24:25], v[24:25], v[38:39] op_sel_hi:[1,0]
	v_pk_mul_f32 v[26:27], v[26:27], v[38:39] op_sel_hi:[1,0]
	v_pk_mul_f32 v[22:23], v[22:23], v[38:39] op_sel_hi:[1,0]
	v_pk_mul_f32 v[20:21], v[20:21], v[38:39] op_sel_hi:[1,0]
	v_pk_mul_f32 v[18:19], v[18:19], v[38:39] op_sel_hi:[1,0]
	v_pk_mul_f32 v[16:17], v[16:17], v[38:39] op_sel_hi:[1,0]
	v_pk_mul_f32 v[14:15], v[14:15], v[38:39] op_sel_hi:[1,0]
	v_pk_mul_f32 v[12:13], v[12:13], v[38:39] op_sel_hi:[1,0]
	v_pk_mul_f32 v[10:11], v[10:11], v[38:39] op_sel_hi:[1,0]
	v_pk_mul_f32 v[8:9], v[8:9], v[38:39] op_sel_hi:[1,0]
	v_pk_mul_f32 v[6:7], v[6:7], v[38:39] op_sel_hi:[1,0]
	v_pk_mul_f32 v[4:5], v[4:5], v[38:39] op_sel_hi:[1,0]
	v_pk_mul_f32 v[2:3], v[2:3], v[38:39] op_sel_hi:[1,0]
	v_pk_mul_f32 v[0:1], v[0:1], v[38:39] op_sel_hi:[1,0]
	s_waitcnt vmcnt(0)
	v_pk_mul_f32 v[24:25], v[32:33], v[24:25]
	v_pk_mul_f32 v[26:27], v[34:35], v[26:27]
	v_cvt_pk_bf16_f32 v24, v24, v25
	v_cvt_pk_bf16_f32 v25, v26, v27
	global_store_dwordx2 v[36:37], v[24:25], off
	v_pk_mul_f32 v[22:23], v[192:193], v[22:23]
	v_pk_mul_f32 v[20:21], v[194:195], v[20:21]
	v_cvt_pk_bf16_f32 v22, v22, v23
	v_cvt_pk_bf16_f32 v23, v20, v21
	global_store_dwordx2 v[36:37], v[22:23], off offset:16
	v_pk_mul_f32 v[18:19], v[196:197], v[18:19]
	v_pk_mul_f32 v[16:17], v[198:199], v[16:17]
	v_cvt_pk_bf16_f32 v18, v18, v19
	v_cvt_pk_bf16_f32 v19, v16, v17
	global_store_dwordx2 v[36:37], v[18:19], off offset:32
	v_pk_mul_f32 v[14:15], v[200:201], v[14:15]
	v_pk_mul_f32 v[12:13], v[202:203], v[12:13]
	v_cvt_pk_bf16_f32 v14, v14, v15
	v_cvt_pk_bf16_f32 v15, v12, v13
	global_store_dwordx2 v[36:37], v[14:15], off offset:48
	v_pk_mul_f32 v[10:11], v[10:11], v[204:205]
	v_pk_mul_f32 v[8:9], v[8:9], v[206:207]
	v_cvt_pk_bf16_f32 v10, v10, v11
	v_cvt_pk_bf16_f32 v11, v8, v9
	global_store_dwordx2 v[36:37], v[10:11], off offset:64
	v_pk_mul_f32 v[6:7], v[6:7], v[208:209]
	v_pk_mul_f32 v[4:5], v[4:5], v[210:211]
	v_cvt_pk_bf16_f32 v6, v6, v7
	v_cvt_pk_bf16_f32 v7, v4, v5
	global_store_dwordx2 v[36:37], v[6:7], off offset:80
	v_pk_mul_f32 v[2:3], v[2:3], v[226:227]
	v_pk_mul_f32 v[0:1], v[0:1], v[228:229]
	v_cvt_pk_bf16_f32 v2, v2, v3
	v_cvt_pk_bf16_f32 v3, v0, v1
	global_store_dwordx2 v[36:37], v[2:3], off offset:96
	v_pk_mul_f32 v[4:5], v[30:31], v[38:39] op_sel_hi:[1,0]
	v_pk_mul_f32 v[6:7], v[28:29], v[38:39] op_sel_hi:[1,0]
	v_pk_mul_f32 v[0:1], v[4:5], v[232:233]
	v_pk_mul_f32 v[2:3], v[6:7], v[234:235]
	v_cvt_pk_bf16_f32 v0, v0, v1
	v_cvt_pk_bf16_f32 v1, v2, v3
	global_store_dwordx2 v[36:37], v[0:1], off offset:112
	s_branch .LBB0_663
